# v121 + W_in epilogue: all eight row-statistic loads issued at the epilogue start instead of two per batch (three exposed load waits per tile removed)
# baseline (speedup 1.0000x reference)
;     __device__ __forceinline__ void operator()(const f32x4 (&acc)[2][2][4][2], const Unit& u, int wr, int wc, int, int) const {
;     ...
;             for (int mm = 0; mm < 2; ++mm) { const int row = row0 + ai * HALF + ((ab & 1) * 2 + mm) * 16;
;                 pq[mm] = *(const v4f*)(ssp + (size_t)row * 16 + 4 * fq);
;                 if (rot) { const v4f* cp = (const v4f*)(cosT + (size_t)row * 32 + 8 * fq); const v4f* sp = (const v4f*)(sinT + (size_t)row * 32 + 8 * fq);
;                     cs[mm][0] = cp[0]; cs[mm][1] = cp[1]; cs[mm][2] = sp[0]; cs[mm][3] = sp[1]; } }
;             asm volatile("" ::: "memory");
; #pragma unroll
;             for (int mm = 0; mm < 2; ++mm) { const int m = (ab & 1) * 2 + mm;
;                 const int row = row0 + ai * HALF + m * 16; const float rs = rstd_from_quarter(pq[mm], fq * 16 + fr);
;                 float v0[8], v1[8];
; #pragma unroll
;                 for (int n = 0; n < 2; ++n)
; #pragma unroll
;                     for (int i = 0; i < 4; ++i) { v0[n * 4 + i] = acc[ai][0][m][n][i] * rs; v1[n * 4 + i] = acc[ai][1][m][n][i] * rs; }
;                 bf16_t* zr = Z + (size_t)row * ZP + (tile < 5 ? tile : 0) * 256;
;                 const int bl_ = row >> 12, sq_ = row & (SEQ - 1);
;                 if (tile >= 5 && tile <= 8) {
;                     const v4f c0 = cs[mm][0], c1 = cs[mm][1], s0 = cs[mm][2], s1 = cs[mm][3];
;                     const float cc[8] = {c0.x, c0.y, c0.z, c0.w, c1.x, c1.y, c1.z, c1.w}, sn[8] = {s0.x, s0.y, s0.z, s0.w, s1.x, s1.y, s1.z, s1.w};
;                     const float qs = tile < 7 ? QC2 : 1.0f;
;                     float o0[8], o1[8];
; #pragma unroll
;                     for (int i = 0; i < 8; ++i) { o0[i] = (v0[i] * cc[i] - v1[i] * sn[i]) * qs; o1[i] = (v1[i] * cc[i] + v0[i] * sn[i]) * qs; }
;                     bf16_t* dst = (tile < 7 ? QC : KC) + ((size_t)((bl_ * 8 + ((tile - 5) & 1) * 4 + wc) * SEQ + sq_)) * 64 + 8 * fq;
;                     *(u32x4*)(dst) = pack8(o0);
;                     *(u32x4*)(dst + 32) = pack8(o1);
;                 } else if (tile == 23) {
;                     if (wc == 0 && fq == 0) {
;                         float* mo = mif + (size_t)row * 8;
;                         *(v4f*)(mo) = (v4f){v0[0] + gate_b[0], v0[1] + gate_b[1], v0[2] + gate_b[2], v0[3] + gate_b[3]};
.LBB0_1137:
	v_lshlrev_b64 v[218:219], 6, v[180:181]
	v_lshl_add_u64 v[218:219], v[182:183], 0, v[218:219]
	global_load_dwordx4 v[206:209], v[218:219], off offset:2048
	global_load_dwordx4 v[210:213], v[218:219], off offset:3072
	v_add_co_u32_e32 v218, vcc, 0x2000, v218
	s_nop 1
	v_addc_co_u32_e32 v219, vcc, 0, v219, vcc
	global_load_dwordx4 v[214:217], v[218:219], off
	global_load_dwordx4 v[222:225], v[218:219], off offset:1024
	global_load_dwordx4 v[226:229], v[218:219], off offset:2048
	global_load_dwordx4 v[240:243], v[218:219], off offset:3072
	v_lshlrev_b32_e32 v191, 2, v191
	v_lshlrev_b32_e32 v220, 3, v190
	v_bitop3_b32 v194, v191, 64, v244 bitop3:0x6c
	v_bitop3_b32 v195, v191, s90, v244 bitop3:0x6c
	v_cmp_eq_u32_e32 vcc, 0, v190
	s_waitcnt vmcnt(0)
	v_mov_b32_e32 v190, v165
	v_mov_b32_e32 v191, v166
	v_mov_b32_e32 v165, v167
	v_pk_add_f32 v[164:165], v[190:191], v[164:165]
	s_lshl_b32 s4, s8, 8
	v_add_f32_e32 v164, v164, v165
	ds_bpermute_b32 v165, v194, v164
	s_cmp_lt_i32 s8, 5
	s_cselect_b32 s88, s4, 0
	s_ashr_i32 s89, s88, 31
	s_cmp_lg_u32 s8, 23
	s_waitcnt lgkmcnt(0)
	v_add_f32_e32 v164, v164, v165
	ds_bpermute_b32 v165, v195, v164
	s_cselect_b64 s[96:97], -1, 0
	s_add_i32 s5, s8, -9
	s_cmp_gt_u32 s5, 1
	s_cselect_b64 s[92:93], -1, 0
	s_waitcnt lgkmcnt(0)
	v_add_f32_e32 v164, v164, v165
	s_cmp_lt_i32 s8, 11
	v_fmamk_f32 v164, v164, 0x3a800000, v235
	s_cselect_b64 s[90:91], -1, 0
	s_and_b64 s[84:85], s[72:73], vcc
	v_cmp_gt_f32_e32 vcc, s25, v164
	v_mul_f32_e32 v165, 0x4b800000, v164
	s_add_i32 s86, s4, 0xfffff500
	v_cndmask_b32_e32 v164, v164, v165, vcc
	v_rsq_f32_e32 v164, v164
	s_lshl_b32 s77, s8, 14
	s_ashr_i32 s87, s86, 31
	s_add_i32 s77, s77, s0
	s_cmp_lt_u32 s8, 7
	s_cselect_b64 s[4:5], -1, 0
	s_ashr_i32 s9, s9, 12
	v_mul_f32_e32 v165, 0x45800000, v164
	s_lshl_b32 s40, s9, 15
	v_cndmask_b32_e32 v196, v164, v165, vcc
	s_add_i32 s40, s40, s77
	v_pk_mul_f32 v[166:167], v[156:157], v[196:197] op_sel_hi:[1,0]
	v_pk_mul_f32 v[190:191], v[148:149], v[196:197] op_sel_hi:[1,0]
	v_pk_mul_f32 v[158:159], v[158:159], v[196:197] op_sel_hi:[1,0]
	v_pk_mul_f32 v[164:165], v[150:151], v[196:197] op_sel_hi:[1,0]
	v_pk_mul_f32 v[152:153], v[152:153], v[196:197] op_sel_hi:[1,0]
	v_pk_mul_f32 v[156:157], v[144:145], v[196:197] op_sel_hi:[1,0]
	v_pk_mul_f32 v[148:149], v[154:155], v[196:197] op_sel_hi:[1,0]
	v_pk_mul_f32 v[150:151], v[146:147], v[196:197] op_sel_hi:[1,0]
	v_and_b32_e32 v147, 0xfcf, v180
	s_mov_b64 s[10:11], -1
	s_and_b64 vcc, exec, s[94:95]
	s_cbranch_vccz .LBB0_1153
	s_and_b64 vcc, exec, s[96:97]
	s_cbranch_vccz .LBB0_1148
	s_and_b64 vcc, exec, s[92:93]
	s_cbranch_vccz .LBB0_1145
	v_mov_b64_e32 v[144:145], s[12:13]
	v_mad_i64_i32 v[144:145], s[10:11], v180, s29, v[144:145]
	s_mov_b64 s[10:11], -1
	s_and_b64 vcc, exec, s[90:91]
	s_cbranch_vccz .LBB0_1142
	v_lshl_add_u64 v[154:155], s[88:89], 1, v[144:145]
	s_lshl_b32 s30, s68, 1
	v_lshl_add_u64 v[154:155], v[154:155], 0, s[30:31]
	v_lshlrev_b32_e32 v200, 1, v220
	v_mov_b32_e32 v201, v221
	v_cvt_pk_bf16_f32 v196, v166, v167
	v_cvt_pk_bf16_f32 v197, v158, v159
	v_cvt_pk_bf16_f32 v198, v152, v153
	v_cvt_pk_bf16_f32 v199, v148, v149
	v_lshl_add_u64 v[154:155], v[154:155], 0, v[200:201]
	global_store_dwordx4 v[154:155], v[196:199], off
	s_mov_b64 s[10:11], 0
	s_nop 0
	v_cvt_pk_bf16_f32 v196, v190, v191
	v_cvt_pk_bf16_f32 v197, v164, v165
	v_cvt_pk_bf16_f32 v198, v156, v157
	v_cvt_pk_bf16_f32 v199, v150, v151
	global_store_dwordx4 v[154:155], v[196:199], off offset:256

;     __device__ __forceinline__ void operator()(const f32x4 (&acc)[2][2][4][2], const Unit& u, int wr, int wc, int, int) const {
;     ...
;             for (int mm = 0; mm < 2; ++mm) { const int row = row0 + ai * HALF + ((ab & 1) * 2 + mm) * 16;
;                 pq[mm] = *(const v4f*)(ssp + (size_t)row * 16 + 4 * fq);
;                 if (rot) { const v4f* cp = (const v4f*)(cosT + (size_t)row * 32 + 8 * fq); const v4f* sp = (const v4f*)(sinT + (size_t)row * 32 + 8 * fq);
;                     cs[mm][0] = cp[0]; cs[mm][1] = cp[1]; cs[mm][2] = sp[0]; cs[mm][3] = sp[1]; } }
;             asm volatile("" ::: "memory");
; #pragma unroll
;             for (int mm = 0; mm < 2; ++mm) { const int m = (ab & 1) * 2 + mm;
;                 const int row = row0 + ai * HALF + m * 16; const float rs = rstd_from_quarter(pq[mm], fq * 16 + fr);
;                 float v0[8], v1[8];
; #pragma unroll
;                 for (int n = 0; n < 2; ++n)
; #pragma unroll
;                     for (int i = 0; i < 4; ++i) { v0[n * 4 + i] = acc[ai][0][m][n][i] * rs; v1[n * 4 + i] = acc[ai][1][m][n][i] * rs; }
.LBB0_1173:
	v_or_b32_e32 v138, 32, v180
	v_ashrrev_i32_e32 v139, 31, v138
	v_lshlrev_b64 v[128:129], 6, v[138:139]
	v_lshl_add_u64 v[128:129], v[182:183], 0, v[128:129]
	s_and_b64 vcc, exec, s[6:7]
	s_cbranch_vccnz .LBB0_1175
	v_lshlrev_b64 v[48:49], 7, v[138:139]
	v_lshl_add_u64 v[52:53], v[184:185], 0, v[48:49]
	v_lshl_add_u64 v[60:61], v[186:187], 0, v[48:49]
	global_load_dwordx4 v[48:51], v[52:53], off offset:16
	s_nop 0
	global_load_dwordx4 v[52:55], v[52:53], off
	s_nop 0
	global_load_dwordx4 v[56:59], v[60:61], off offset:16
	s_nop 0
	global_load_dwordx4 v[60:63], v[60:61], off
.LBB0_1175:
	v_or_b32_e32 v136, 48, v180
	v_ashrrev_i32_e32 v137, 31, v136
	v_lshlrev_b64 v[128:129], 6, v[136:137]
	v_lshl_add_u64 v[128:129], v[182:183], 0, v[128:129]
	s_and_b64 vcc, exec, s[6:7]
	s_cbranch_vccnz .LBB0_1177
	v_lshlrev_b64 v[16:17], 7, v[136:137]
	v_lshl_add_u64 v[20:21], v[184:185], 0, v[16:17]
	v_lshl_add_u64 v[32:33], v[186:187], 0, v[16:17]
	global_load_dwordx4 v[16:19], v[20:21], off offset:16
	s_nop 0
	global_load_dwordx4 v[20:23], v[20:21], off
	s_nop 0
	global_load_dwordx4 v[24:27], v[32:33], off offset:16
	s_nop 0
	global_load_dwordx4 v[32:35], v[32:33], off
	s_waitcnt vmcnt(0)
.LBB0_1177:
	v_mov_b32_e32 v132, v206
	v_mov_b32_e32 v133, v207
	v_mov_b32_e32 v134, v208
	v_mov_b32_e32 v135, v209
	v_mov_b32_e32 v140, v133
	v_mov_b32_e32 v141, v134
	v_mov_b32_e32 v133, v135
	v_pk_add_f32 v[132:133], v[140:141], v[132:133]
	s_mov_b64 s[22:23], -1
	v_add_f32_e32 v132, v132, v133
	ds_bpermute_b32 v133, v194, v132
	s_waitcnt lgkmcnt(0)
	v_add_f32_e32 v132, v132, v133
	ds_bpermute_b32 v133, v195, v132
	s_waitcnt lgkmcnt(0)
	v_add_f32_e32 v132, v132, v133
	v_fmamk_f32 v132, v132, 0x3a800000, v235
	v_mul_f32_e32 v133, 0x4b800000, v132
	v_cmp_gt_f32_e32 vcc, s25, v132
	s_nop 1
	v_cndmask_b32_e32 v132, v132, v133, vcc
	v_rsq_f32_e32 v132, v132
	s_nop 0
	v_mul_f32_e32 v133, 0x45800000, v132
	v_cndmask_b32_e32 v140, v132, v133, vcc
	v_pk_mul_f32 v[132:133], v[124:125], v[140:141] op_sel_hi:[1,0]
	v_pk_mul_f32 v[134:135], v[116:117], v[140:141] op_sel_hi:[1,0]
	v_pk_mul_f32 v[124:125], v[126:127], v[140:141] op_sel_hi:[1,0]
	v_pk_mul_f32 v[126:127], v[118:119], v[140:141] op_sel_hi:[1,0]
	v_pk_mul_f32 v[116:117], v[120:121], v[140:141] op_sel_hi:[1,0]
	v_pk_mul_f32 v[118:119], v[112:113], v[140:141] op_sel_hi:[1,0]
	v_pk_mul_f32 v[112:113], v[122:123], v[140:141] op_sel_hi:[1,0]
	v_pk_mul_f32 v[114:115], v[114:115], v[140:141] op_sel_hi:[1,0]
	v_and_b32_e32 v122, 0xfef, v138
	s_and_b64 vcc, exec, s[10:11]
	s_cbranch_vccnz .LBB0_1193
	s_and_b64 vcc, exec, s[8:9]
	s_cbranch_vccnz .LBB0_1188
	s_andn2_b64 vcc, exec, s[92:93]
	s_cbranch_vccnz .LBB0_1185
	v_mov_b64_e32 v[120:121], s[12:13]
	v_mad_i64_i32 v[120:121], s[22:23], v138, s29, v[120:121]
	s_andn2_b64 vcc, exec, s[90:91]
	s_mov_b64 s[22:23], -1
	s_cbranch_vccnz .LBB0_1182
	v_lshl_add_u64 v[148:149], s[88:89], 1, v[120:121]
	s_lshl_b32 s30, s68, 1
	v_lshl_add_u64 v[148:149], v[148:149], 0, s[30:31]
	v_mov_b32_e32 v145, v221
	v_cvt_pk_bf16_f32 v140, v132, v133
	v_cvt_pk_bf16_f32 v141, v124, v125
	v_cvt_pk_bf16_f32 v142, v116, v117
	v_cvt_pk_bf16_f32 v143, v112, v113
	v_lshl_add_u64 v[148:149], v[148:149], 0, v[144:145]
	global_store_dwordx4 v[148:149], v[140:143], off
	s_mov_b64 s[22:23], 0
	s_nop 0
	v_cvt_pk_bf16_f32 v140, v134, v135
	v_cvt_pk_bf16_f32 v141, v126, v127
	v_cvt_pk_bf16_f32 v142, v118, v119
	v_cvt_pk_bf16_f32 v143, v114, v115
	global_store_dwordx4 v[148:149], v[140:143], off offset:256

;     __device__ __forceinline__ void operator()(const f32x4 (&acc)[2][2][4][2], const Unit& u, int wr, int wc, int, int) const {
;     ...
;             for (int mm = 0; mm < 2; ++mm) { const int m = (ab & 1) * 2 + mm;
;                 const int row = row0 + ai * HALF + m * 16; const float rs = rstd_from_quarter(pq[mm], fq * 16 + fr);
;                 float v0[8], v1[8];
; #pragma unroll
;                 for (int n = 0; n < 2; ++n)
; #pragma unroll
;                     for (int i = 0; i < 4; ++i) { v0[n * 4 + i] = acc[ai][0][m][n][i] * rs; v1[n * 4 + i] = acc[ai][1][m][n][i] * rs; }
.LBB0_1195:
	v_mov_b32_e32 v128, v210
	v_mov_b32_e32 v129, v211
	v_mov_b32_e32 v130, v212
	v_mov_b32_e32 v131, v213
	s_nop 0
	v_mov_b32_e32 v112, v129
	v_mov_b32_e32 v113, v130
	v_mov_b32_e32 v129, v131
	v_pk_add_f32 v[112:113], v[112:113], v[128:129]
	v_and_b32_e32 v116, 0xfff, v136
	v_add_f32_e32 v112, v112, v113
	ds_bpermute_b32 v113, v194, v112
	s_mov_b64 s[22:23], -1
	s_waitcnt lgkmcnt(0)
	v_add_f32_e32 v112, v112, v113
	ds_bpermute_b32 v113, v195, v112
	s_waitcnt lgkmcnt(0)
	v_add_f32_e32 v112, v112, v113
	v_fmamk_f32 v112, v112, 0x3a800000, v235
	v_mul_f32_e32 v113, 0x4b800000, v112
	v_cmp_gt_f32_e32 vcc, s25, v112
	s_nop 1
	v_cndmask_b32_e32 v112, v112, v113, vcc
	v_rsq_f32_e32 v112, v112
	s_nop 0
	v_mul_f32_e32 v113, 0x45800000, v112
	v_cndmask_b32_e32 v118, v112, v113, vcc
	v_pk_mul_f32 v[112:113], v[108:109], v[118:119] op_sel_hi:[1,0]
	v_pk_mul_f32 v[114:115], v[100:101], v[118:119] op_sel_hi:[1,0]
	v_pk_mul_f32 v[108:109], v[110:111], v[118:119] op_sel_hi:[1,0]
	v_pk_mul_f32 v[110:111], v[102:103], v[118:119] op_sel_hi:[1,0]
	v_pk_mul_f32 v[100:101], v[104:105], v[118:119] op_sel_hi:[1,0]
	v_pk_mul_f32 v[102:103], v[96:97], v[118:119] op_sel_hi:[1,0]
	v_pk_mul_f32 v[96:97], v[106:107], v[118:119] op_sel_hi:[1,0]
	v_pk_mul_f32 v[98:99], v[98:99], v[118:119] op_sel_hi:[1,0]
	s_and_b64 vcc, exec, s[10:11]
	s_cbranch_vccnz .LBB0_1211
	s_and_b64 vcc, exec, s[8:9]
	s_cbranch_vccnz .LBB0_1206
	s_andn2_b64 vcc, exec, s[92:93]
	s_cbranch_vccnz .LBB0_1203
	v_mov_b64_e32 v[104:105], s[12:13]
	v_mad_i64_i32 v[104:105], s[22:23], v136, s29, v[104:105]
	s_andn2_b64 vcc, exec, s[90:91]
	s_mov_b64 s[22:23], -1
	s_cbranch_vccnz .LBB0_1200
	v_lshl_add_u64 v[106:107], s[88:89], 1, v[104:105]
	s_lshl_b32 s30, s68, 1
	v_lshl_add_u64 v[106:107], v[106:107], 0, s[30:31]
	v_mov_b32_e32 v145, v221
	v_cvt_pk_bf16_f32 v118, v112, v113
	v_cvt_pk_bf16_f32 v119, v108, v109
	v_cvt_pk_bf16_f32 v120, v100, v101
	v_cvt_pk_bf16_f32 v121, v96, v97
	v_lshl_add_u64 v[106:107], v[106:107], 0, v[144:145]
	global_store_dwordx4 v[106:107], v[118:121], off
	s_mov_b64 s[22:23], 0
	s_nop 0
	v_cvt_pk_bf16_f32 v118, v114, v115
	v_cvt_pk_bf16_f32 v119, v110, v111
	v_cvt_pk_bf16_f32 v120, v102, v103
	v_cvt_pk_bf16_f32 v121, v98, v99
	global_store_dwordx4 v[106:107], v[118:121], off offset:256

;     __device__ __forceinline__ void operator()(const f32x4 (&acc)[2][2][4][2], const Unit& u, int wr, int wc, int, int) const {
;     ...
;             for (int mm = 0; mm < 2; ++mm) { const int row = row0 + ai * HALF + ((ab & 1) * 2 + mm) * 16;
;                 pq[mm] = *(const v4f*)(ssp + (size_t)row * 16 + 4 * fq);
;                 if (rot) { const v4f* cp = (const v4f*)(cosT + (size_t)row * 32 + 8 * fq); const v4f* sp = (const v4f*)(sinT + (size_t)row * 32 + 8 * fq);
;                     cs[mm][0] = cp[0]; cs[mm][1] = cp[1]; cs[mm][2] = sp[0]; cs[mm][3] = sp[1]; } }
;             asm volatile("" ::: "memory");
; #pragma unroll
;             for (int mm = 0; mm < 2; ++mm) { const int m = (ab & 1) * 2 + mm;
;                 const int row = row0 + ai * HALF + m * 16; const float rs = rstd_from_quarter(pq[mm], fq * 16 + fr);
;                 float v0[8], v1[8];
; #pragma unroll
;                 for (int n = 0; n < 2; ++n)
; #pragma unroll
;                     for (int i = 0; i < 4; ++i) { v0[n * 4 + i] = acc[ai][0][m][n][i] * rs; v1[n * 4 + i] = acc[ai][1][m][n][i] * rs; }
.LBB0_1213:
	v_add_u32_e32 v106, 0x80, v180
	v_ashrrev_i32_e32 v107, 31, v106
	v_lshlrev_b64 v[96:97], 6, v[106:107]
	v_lshl_add_u64 v[96:97], v[182:183], 0, v[96:97]
	s_and_b64 vcc, exec, s[6:7]
	s_cbranch_vccnz .LBB0_1215
	v_lshlrev_b64 v[48:49], 7, v[106:107]
	v_lshl_add_u64 v[52:53], v[184:185], 0, v[48:49]
	v_lshl_add_u64 v[60:61], v[186:187], 0, v[48:49]
	global_load_dwordx4 v[48:51], v[52:53], off offset:16
	s_nop 0
	global_load_dwordx4 v[52:55], v[52:53], off
	s_nop 0
	global_load_dwordx4 v[56:59], v[60:61], off offset:16
	s_nop 0
	global_load_dwordx4 v[60:63], v[60:61], off
.LBB0_1215:
	v_add_u32_e32 v104, 0x90, v180
	v_ashrrev_i32_e32 v105, 31, v104
	v_lshlrev_b64 v[96:97], 6, v[104:105]
	v_lshl_add_u64 v[96:97], v[182:183], 0, v[96:97]
	s_and_b64 vcc, exec, s[6:7]
	s_cbranch_vccnz .LBB0_1217
	v_lshlrev_b64 v[16:17], 7, v[104:105]
	v_lshl_add_u64 v[20:21], v[184:185], 0, v[16:17]
	v_lshl_add_u64 v[32:33], v[186:187], 0, v[16:17]
	global_load_dwordx4 v[16:19], v[20:21], off offset:16
	s_nop 0
	global_load_dwordx4 v[20:23], v[20:21], off
	s_nop 0
	global_load_dwordx4 v[24:27], v[32:33], off offset:16
	s_nop 0
	global_load_dwordx4 v[32:35], v[32:33], off
	s_waitcnt vmcnt(0)
.LBB0_1217:
	v_mov_b32_e32 v100, v214
	v_mov_b32_e32 v101, v215
	v_mov_b32_e32 v102, v216
	v_mov_b32_e32 v103, v217
	v_mov_b32_e32 v110, v101
	v_mov_b32_e32 v111, v102
	v_mov_b32_e32 v101, v103
	v_pk_add_f32 v[100:101], v[110:111], v[100:101]
	v_ashrrev_i32_e32 v109, 12, v106
	v_add_f32_e32 v100, v100, v101
	ds_bpermute_b32 v101, v194, v100
	v_lshl_add_u32 v108, v109, 15, s77
	s_mov_b64 s[94:95], -1
	s_waitcnt lgkmcnt(0)
	v_add_f32_e32 v100, v100, v101
	ds_bpermute_b32 v101, v195, v100
	s_waitcnt lgkmcnt(0)
	v_add_f32_e32 v100, v100, v101
	v_fmamk_f32 v100, v100, 0x3a800000, v235
	v_cmp_gt_f32_e32 vcc, s25, v100
	v_mul_f32_e32 v101, 0x4b800000, v100
	s_nop 0
	v_cndmask_b32_e32 v100, v100, v101, vcc
	v_rsq_f32_e32 v100, v100
	s_nop 0
	v_mul_f32_e32 v101, 0x45800000, v100
	v_cndmask_b32_e32 v110, v100, v101, vcc
	v_pk_mul_f32 v[100:101], v[92:93], v[110:111] op_sel_hi:[1,0]
	v_pk_mul_f32 v[102:103], v[84:85], v[110:111] op_sel_hi:[1,0]
	v_pk_mul_f32 v[92:93], v[94:95], v[110:111] op_sel_hi:[1,0]
	v_pk_mul_f32 v[94:95], v[86:87], v[110:111] op_sel_hi:[1,0]
	v_pk_mul_f32 v[84:85], v[88:89], v[110:111] op_sel_hi:[1,0]
	v_pk_mul_f32 v[86:87], v[80:81], v[110:111] op_sel_hi:[1,0]
	v_pk_mul_f32 v[80:81], v[90:91], v[110:111] op_sel_hi:[1,0]
	v_pk_mul_f32 v[82:83], v[82:83], v[110:111] op_sel_hi:[1,0]
	v_and_b32_e32 v90, 0xfcf, v106
	s_and_b64 vcc, exec, s[10:11]
	s_cbranch_vccnz .LBB0_1233
	s_and_b64 vcc, exec, s[8:9]
	s_mov_b64 s[22:23], -1
	s_cbranch_vccnz .LBB0_1228
	s_andn2_b64 vcc, exec, s[92:93]
	s_cbranch_vccnz .LBB0_1225
	v_mov_b64_e32 v[88:89], s[12:13]
	v_mad_i64_i32 v[88:89], s[22:23], v106, s29, v[88:89]
	s_andn2_b64 vcc, exec, s[90:91]
	s_mov_b64 s[22:23], -1
	s_cbranch_vccnz .LBB0_1222
	v_lshl_add_u64 v[114:115], s[88:89], 1, v[88:89]
	s_lshl_b32 s30, s68, 1
	v_lshl_add_u64 v[114:115], v[114:115], 0, s[30:31]
	v_mov_b32_e32 v145, v221
	v_cvt_pk_bf16_f32 v110, v100, v101
	v_cvt_pk_bf16_f32 v111, v92, v93
	v_cvt_pk_bf16_f32 v112, v84, v85
	v_cvt_pk_bf16_f32 v113, v80, v81
	v_lshl_add_u64 v[114:115], v[114:115], 0, v[144:145]
	global_store_dwordx4 v[114:115], v[110:113], off
	s_mov_b64 s[22:23], 0
	s_nop 0
	v_cvt_pk_bf16_f32 v110, v102, v103
	v_cvt_pk_bf16_f32 v111, v94, v95
	v_cvt_pk_bf16_f32 v112, v86, v87
	v_cvt_pk_bf16_f32 v113, v82, v83
	global_store_dwordx4 v[114:115], v[110:113], off offset:256

;     __device__ __forceinline__ void operator()(const f32x4 (&acc)[2][2][4][2], const Unit& u, int wr, int wc, int, int) const {
;     ...
;             for (int mm = 0; mm < 2; ++mm) { const int m = (ab & 1) * 2 + mm;
;                 const int row = row0 + ai * HALF + m * 16; const float rs = rstd_from_quarter(pq[mm], fq * 16 + fr);
;                 float v0[8], v1[8];
; #pragma unroll
;                 for (int n = 0; n < 2; ++n)
; #pragma unroll
;                     for (int i = 0; i < 4; ++i) { v0[n * 4 + i] = acc[ai][0][m][n][i] * rs; v1[n * 4 + i] = acc[ai][1][m][n][i] * rs; }
.LBB0_1235:
	v_mov_b32_e32 v96, v222
	v_mov_b32_e32 v97, v223
	v_mov_b32_e32 v98, v224
	v_mov_b32_e32 v99, v225
	s_nop 0
	v_mov_b32_e32 v80, v97
	v_mov_b32_e32 v81, v98
	v_mov_b32_e32 v97, v99
	v_pk_add_f32 v[80:81], v[80:81], v[96:97]
	v_and_b32_e32 v84, 0xfdf, v104
	v_add_f32_e32 v80, v80, v81
	ds_bpermute_b32 v81, v194, v80
	s_mov_b64 s[22:23], -1
	s_waitcnt lgkmcnt(0)
	v_add_f32_e32 v80, v80, v81
	ds_bpermute_b32 v81, v195, v80
	s_waitcnt lgkmcnt(0)
	v_add_f32_e32 v80, v80, v81
	v_fmamk_f32 v80, v80, 0x3a800000, v235
	v_mul_f32_e32 v81, 0x4b800000, v80
	v_cmp_gt_f32_e32 vcc, s25, v80
	s_nop 1
	v_cndmask_b32_e32 v80, v80, v81, vcc
	v_rsq_f32_e32 v80, v80
	s_nop 0
	v_mul_f32_e32 v81, 0x45800000, v80
	v_cndmask_b32_e32 v86, v80, v81, vcc
	v_pk_mul_f32 v[80:81], v[76:77], v[86:87] op_sel_hi:[1,0]
	v_pk_mul_f32 v[82:83], v[68:69], v[86:87] op_sel_hi:[1,0]
	v_pk_mul_f32 v[76:77], v[78:79], v[86:87] op_sel_hi:[1,0]
	v_pk_mul_f32 v[78:79], v[70:71], v[86:87] op_sel_hi:[1,0]
	v_pk_mul_f32 v[68:69], v[72:73], v[86:87] op_sel_hi:[1,0]
	v_pk_mul_f32 v[70:71], v[64:65], v[86:87] op_sel_hi:[1,0]
	v_pk_mul_f32 v[64:65], v[74:75], v[86:87] op_sel_hi:[1,0]
	v_pk_mul_f32 v[66:67], v[66:67], v[86:87] op_sel_hi:[1,0]
	s_and_b64 vcc, exec, s[10:11]
	s_cbranch_vccnz .LBB0_1251
	s_and_b64 vcc, exec, s[8:9]
	s_cbranch_vccnz .LBB0_1246
	s_andn2_b64 vcc, exec, s[92:93]
	s_cbranch_vccnz .LBB0_1243
	v_mov_b64_e32 v[72:73], s[12:13]
	v_mad_i64_i32 v[72:73], s[22:23], v104, s29, v[72:73]
	s_andn2_b64 vcc, exec, s[90:91]
	s_mov_b64 s[22:23], -1
	s_cbranch_vccnz .LBB0_1240
	v_lshl_add_u64 v[74:75], s[88:89], 1, v[72:73]
	s_lshl_b32 s30, s68, 1
	v_lshl_add_u64 v[74:75], v[74:75], 0, s[30:31]
	v_mov_b32_e32 v145, v221
	v_cvt_pk_bf16_f32 v90, v80, v81
	v_cvt_pk_bf16_f32 v91, v76, v77
	v_cvt_pk_bf16_f32 v92, v68, v69
	v_cvt_pk_bf16_f32 v93, v64, v65
	v_lshl_add_u64 v[74:75], v[74:75], 0, v[144:145]
	global_store_dwordx4 v[74:75], v[90:93], off
	s_mov_b64 s[22:23], 0
	s_nop 0
	v_cvt_pk_bf16_f32 v90, v82, v83
	v_cvt_pk_bf16_f32 v91, v78, v79
	v_cvt_pk_bf16_f32 v92, v70, v71
	v_cvt_pk_bf16_f32 v93, v66, v67
	global_store_dwordx4 v[74:75], v[90:93], off offset:256

;     __device__ __forceinline__ void operator()(const f32x4 (&acc)[2][2][4][2], const Unit& u, int wr, int wc, int, int) const {
;     ...
;             for (int mm = 0; mm < 2; ++mm) { const int row = row0 + ai * HALF + ((ab & 1) * 2 + mm) * 16;
;                 pq[mm] = *(const v4f*)(ssp + (size_t)row * 16 + 4 * fq);
;                 if (rot) { const v4f* cp = (const v4f*)(cosT + (size_t)row * 32 + 8 * fq); const v4f* sp = (const v4f*)(sinT + (size_t)row * 32 + 8 * fq);
;                     cs[mm][0] = cp[0]; cs[mm][1] = cp[1]; cs[mm][2] = sp[0]; cs[mm][3] = sp[1]; } }
;             asm volatile("" ::: "memory");
; #pragma unroll
;             for (int mm = 0; mm < 2; ++mm) { const int m = (ab & 1) * 2 + mm;
;                 const int row = row0 + ai * HALF + m * 16; const float rs = rstd_from_quarter(pq[mm], fq * 16 + fr);
;                 float v0[8], v1[8];
; #pragma unroll
;                 for (int n = 0; n < 2; ++n)
; #pragma unroll
;                     for (int i = 0; i < 4; ++i) { v0[n * 4 + i] = acc[ai][0][m][n][i] * rs; v1[n * 4 + i] = acc[ai][1][m][n][i] * rs; }
.LBB0_1253:
	v_add_u32_e32 v74, 0xa0, v180
	v_ashrrev_i32_e32 v75, 31, v74
	v_lshlrev_b64 v[64:65], 6, v[74:75]
	v_lshl_add_u64 v[64:65], v[182:183], 0, v[64:65]
	s_and_b64 vcc, exec, s[6:7]
	s_cbranch_vccnz .LBB0_1255
	v_lshlrev_b64 v[48:49], 7, v[74:75]
	v_lshl_add_u64 v[52:53], v[184:185], 0, v[48:49]
	v_lshl_add_u64 v[60:61], v[186:187], 0, v[48:49]
	global_load_dwordx4 v[48:51], v[52:53], off offset:16
	s_nop 0
	global_load_dwordx4 v[52:55], v[52:53], off
	s_nop 0
	global_load_dwordx4 v[56:59], v[60:61], off offset:16
	s_nop 0
	global_load_dwordx4 v[60:63], v[60:61], off
.LBB0_1255:
	v_add_u32_e32 v72, 0xb0, v180
	v_ashrrev_i32_e32 v73, 31, v72
	v_lshlrev_b64 v[64:65], 6, v[72:73]
	v_lshl_add_u64 v[64:65], v[182:183], 0, v[64:65]
	s_and_b64 vcc, exec, s[6:7]
	s_cbranch_vccnz .LBB0_1257
	v_lshlrev_b64 v[16:17], 7, v[72:73]
	v_lshl_add_u64 v[20:21], v[184:185], 0, v[16:17]
	v_lshl_add_u64 v[32:33], v[186:187], 0, v[16:17]
	global_load_dwordx4 v[16:19], v[20:21], off offset:16
	s_nop 0
	global_load_dwordx4 v[20:23], v[20:21], off
	s_nop 0
	global_load_dwordx4 v[24:27], v[32:33], off offset:16
	s_nop 0
	global_load_dwordx4 v[32:35], v[32:33], off
	s_waitcnt vmcnt(0)
.LBB0_1257:
	v_mov_b32_e32 v68, v226
	v_mov_b32_e32 v69, v227
	v_mov_b32_e32 v70, v228
	v_mov_b32_e32 v71, v229
	v_mov_b32_e32 v76, v69
	v_mov_b32_e32 v77, v70
	v_mov_b32_e32 v69, v71
	v_pk_add_f32 v[68:69], v[76:77], v[68:69]
	s_mov_b64 s[6:7], -1
	v_add_f32_e32 v68, v68, v69
	ds_bpermute_b32 v69, v194, v68
	s_waitcnt lgkmcnt(0)
	v_add_f32_e32 v68, v68, v69
	ds_bpermute_b32 v69, v195, v68
	s_waitcnt lgkmcnt(0)
	v_add_f32_e32 v68, v68, v69
	v_fmamk_f32 v68, v68, 0x3a800000, v235
	v_mul_f32_e32 v69, 0x4b800000, v68
	v_cmp_gt_f32_e32 vcc, s25, v68
	s_nop 1
	v_cndmask_b32_e32 v68, v68, v69, vcc
	v_rsq_f32_e32 v68, v68
	s_nop 0
	v_mul_f32_e32 v69, 0x45800000, v68
	v_cndmask_b32_e32 v76, v68, v69, vcc
	v_pk_mul_f32 v[68:69], v[44:45], v[76:77] op_sel_hi:[1,0]
	v_pk_mul_f32 v[70:71], v[36:37], v[76:77] op_sel_hi:[1,0]
	v_pk_mul_f32 v[44:45], v[46:47], v[76:77] op_sel_hi:[1,0]
	v_pk_mul_f32 v[46:47], v[38:39], v[76:77] op_sel_hi:[1,0]
	v_pk_mul_f32 v[36:37], v[40:41], v[76:77] op_sel_hi:[1,0]
	v_pk_mul_f32 v[38:39], v[28:29], v[76:77] op_sel_hi:[1,0]
	v_pk_mul_f32 v[28:29], v[42:43], v[76:77] op_sel_hi:[1,0]
	v_pk_mul_f32 v[30:31], v[30:31], v[76:77] op_sel_hi:[1,0]
	v_and_b32_e32 v42, 0xfef, v74
	s_and_b64 vcc, exec, s[10:11]
	s_cbranch_vccnz .LBB0_1273
	s_and_b64 vcc, exec, s[8:9]
	s_cbranch_vccnz .LBB0_1268
	s_andn2_b64 vcc, exec, s[92:93]
	s_cbranch_vccnz .LBB0_1265
	v_mov_b64_e32 v[40:41], s[12:13]
	v_mad_i64_i32 v[40:41], s[6:7], v74, s29, v[40:41]
	s_andn2_b64 vcc, exec, s[90:91]
	s_mov_b64 s[6:7], -1
	s_cbranch_vccnz .LBB0_1262
	v_lshl_add_u64 v[80:81], s[88:89], 1, v[40:41]
	s_lshl_b32 s30, s68, 1
	v_lshl_add_u64 v[80:81], v[80:81], 0, s[30:31]
	v_mov_b32_e32 v145, v221
	v_cvt_pk_bf16_f32 v76, v68, v69
	v_cvt_pk_bf16_f32 v77, v44, v45
	v_cvt_pk_bf16_f32 v78, v36, v37
	v_cvt_pk_bf16_f32 v79, v28, v29
	v_lshl_add_u64 v[80:81], v[80:81], 0, v[144:145]
	global_store_dwordx4 v[80:81], v[76:79], off
	s_mov_b64 s[6:7], 0
	s_nop 0
	v_cvt_pk_bf16_f32 v76, v70, v71
	v_cvt_pk_bf16_f32 v77, v46, v47
	v_cvt_pk_bf16_f32 v78, v38, v39
	v_cvt_pk_bf16_f32 v79, v30, v31
	global_store_dwordx4 v[80:81], v[76:79], off offset:256

;     __device__ __forceinline__ void operator()(const f32x4 (&acc)[2][2][4][2], const Unit& u, int wr, int wc, int, int) const {
;     ...
;             for (int mm = 0; mm < 2; ++mm) { const int m = (ab & 1) * 2 + mm;
;                 const int row = row0 + ai * HALF + m * 16; const float rs = rstd_from_quarter(pq[mm], fq * 16 + fr);
;                 float v0[8], v1[8];
; #pragma unroll
;                 for (int n = 0; n < 2; ++n)
; #pragma unroll
;                     for (int i = 0; i < 4; ++i) { v0[n * 4 + i] = acc[ai][0][m][n][i] * rs; v1[n * 4 + i] = acc[ai][1][m][n][i] * rs; }
.LBB0_1275:
	v_mov_b32_e32 v64, v240
	v_mov_b32_e32 v65, v241
	v_mov_b32_e32 v66, v242
	v_mov_b32_e32 v67, v243
	s_nop 0
	v_mov_b32_e32 v28, v65
	v_mov_b32_e32 v29, v66
	v_mov_b32_e32 v65, v67
	v_pk_add_f32 v[28:29], v[28:29], v[64:65]
	v_and_b32_e32 v36, 0xfff, v72
	v_add_f32_e32 v28, v28, v29
	ds_bpermute_b32 v29, v194, v28
	s_mov_b64 s[6:7], -1
	s_waitcnt lgkmcnt(0)
	v_add_f32_e32 v28, v28, v29
	ds_bpermute_b32 v29, v195, v28
	s_waitcnt lgkmcnt(0)
	v_add_f32_e32 v28, v28, v29
	v_fmamk_f32 v28, v28, 0x3a800000, v235
	v_mul_f32_e32 v29, 0x4b800000, v28
	v_cmp_gt_f32_e32 vcc, s25, v28
	s_nop 1
	v_cndmask_b32_e32 v28, v28, v29, vcc
	v_rsq_f32_e32 v28, v28
	s_nop 0
	v_mul_f32_e32 v29, 0x45800000, v28
	v_cndmask_b32_e32 v38, v28, v29, vcc
	v_pk_mul_f32 v[28:29], v[12:13], v[38:39] op_sel_hi:[1,0]
	v_pk_mul_f32 v[30:31], v[4:5], v[38:39] op_sel_hi:[1,0]
	v_pk_mul_f32 v[12:13], v[14:15], v[38:39] op_sel_hi:[1,0]
	v_pk_mul_f32 v[14:15], v[6:7], v[38:39] op_sel_hi:[1,0]
	v_pk_mul_f32 v[4:5], v[8:9], v[38:39] op_sel_hi:[1,0]
	v_pk_mul_f32 v[6:7], v[0:1], v[38:39] op_sel_hi:[1,0]
	v_pk_mul_f32 v[0:1], v[10:11], v[38:39] op_sel_hi:[1,0]
	v_pk_mul_f32 v[2:3], v[2:3], v[38:39] op_sel_hi:[1,0]
	s_and_b64 vcc, exec, s[10:11]
	s_cbranch_vccnz .LBB0_1291
	s_and_b64 vcc, exec, s[8:9]
	s_cbranch_vccnz .LBB0_1286
	s_andn2_b64 vcc, exec, s[92:93]
	s_cbranch_vccnz .LBB0_1283
	v_mov_b64_e32 v[8:9], s[12:13]
	v_mad_i64_i32 v[8:9], s[6:7], v72, s29, v[8:9]
	s_andn2_b64 vcc, exec, s[90:91]
	s_mov_b64 s[6:7], -1
	s_cbranch_vccnz .LBB0_1280
	v_lshl_add_u64 v[10:11], s[88:89], 1, v[8:9]
	s_lshl_b32 s30, s68, 1
	v_lshl_add_u64 v[10:11], v[10:11], 0, s[30:31]
	v_mov_b32_e32 v145, v221
	v_cvt_pk_bf16_f32 v38, v28, v29
	v_cvt_pk_bf16_f32 v39, v12, v13
	v_cvt_pk_bf16_f32 v40, v4, v5
	v_cvt_pk_bf16_f32 v41, v0, v1
	v_lshl_add_u64 v[10:11], v[10:11], 0, v[144:145]
	global_store_dwordx4 v[10:11], v[38:41], off
	s_mov_b64 s[6:7], 0
	s_nop 0
	v_cvt_pk_bf16_f32 v38, v30, v31
	v_cvt_pk_bf16_f32 v39, v14, v15
	v_cvt_pk_bf16_f32 v40, v6, v7
	v_cvt_pk_bf16_f32 v41, v2, v3
	global_store_dwordx4 v[10:11], v[38:41], off offset:256
